# v6 + K-fragment prefetch (counted lgkmcnt) at the serialized QK^T sites of the diagonal loop (attn0) and both attn1 loops
# speedup vs baseline: 1.0149x; 1.0027x over previous
.LBB0_325:
	s_add_u32 s4, s58, 0xffffc000
	s_addc_u32 s5, s59, -1
	s_add_i32 s70, s69, s97
	s_mov_b32 s71, m0
	s_mov_b32 m0, s70
	s_nop 0
	global_load_lds_dwordx4 v199, s[4:5]
	s_mov_b32 m0, s71
	s_addk_i32 s70, 0x400
	s_mov_b32 s71, m0
	s_mov_b32 m0, s70
	s_nop 0
	global_load_lds_dwordx4 v200, s[4:5]
	s_mov_b32 m0, s71
	s_add_i32 s4, s57, 64
	s_cmp_le_i32 s4, s6
	s_cselect_b64 s[70:71], -1, 0
	s_cmp_gt_i32 s4, s6
	s_cbranch_scc1 .LBB0_327
	s_add_i32 s4, s83, 0
	v_add3_u32 v6, s4, v209, v208
	v_add3_u32 v7, s4, v210, v208
	v_add3_u32 v8, s4, v211, v208
	v_add3_u32 v9, s4, v212, v208
	s_setprio 1
	ds_read_b128 v[2:5], v6 offset:49152
	ds_read_b128 v[234:237], v6 offset:57344
	ds_read_b128 v[238:241], v7 offset:49152
	ds_read_b128 v[242:245], v7 offset:57344
	ds_read_b128 v[246:249], v8 offset:49152
	s_waitcnt lgkmcnt(4)
	v_mfma_f32_32x32x16_bf16 v[112:127], v[2:5], v[188:191], 0
	ds_read_b128 v[2:5], v8 offset:57344
	s_waitcnt lgkmcnt(4)
	v_mfma_f32_32x32x16_bf16 v[96:111], v[234:237], v[188:191], 0
	ds_read_b128 v[234:237], v9 offset:49152
	s_waitcnt lgkmcnt(4)
	v_mfma_f32_32x32x16_bf16 v[112:127], v[238:241], v[184:187], v[112:127]
	ds_read_b128 v[238:241], v9 offset:57344
	s_waitcnt lgkmcnt(4)
	v_mfma_f32_32x32x16_bf16 v[96:111], v[242:245], v[184:187], v[96:111]
	ds_read_b128 v[242:245], v6 offset:49280
	s_waitcnt lgkmcnt(4)
	v_mfma_f32_32x32x16_bf16 v[112:127], v[246:249], v[180:183], v[112:127]
	ds_read_b128 v[246:249], v6 offset:57472
	s_waitcnt lgkmcnt(4)
	v_mfma_f32_32x32x16_bf16 v[96:111], v[2:5], v[180:183], v[96:111]
	ds_read_b128 v[2:5], v7 offset:49280
	s_waitcnt lgkmcnt(4)
	v_mfma_f32_32x32x16_bf16 v[112:127], v[234:237], v[176:179], v[112:127]
	ds_read_b128 v[234:237], v7 offset:57472
	s_waitcnt lgkmcnt(4)
	v_mfma_f32_32x32x16_bf16 v[96:111], v[238:241], v[176:179], v[96:111]
	ds_read_b128 v[238:241], v8 offset:49280
	s_waitcnt lgkmcnt(4)
	v_mfma_f32_32x32x16_bf16 v[112:127], v[242:245], v[172:175], v[112:127]
	ds_read_b128 v[242:245], v8 offset:57472
	s_waitcnt lgkmcnt(4)
	v_mfma_f32_32x32x16_bf16 v[96:111], v[246:249], v[172:175], v[96:111]
	ds_read_b128 v[246:249], v9 offset:49280
	s_waitcnt lgkmcnt(4)
	v_mfma_f32_32x32x16_bf16 v[112:127], v[2:5], v[168:171], v[112:127]
	ds_read_b128 v[2:5], v9 offset:57472
	s_waitcnt lgkmcnt(4)
	v_mfma_f32_32x32x16_bf16 v[96:111], v[234:237], v[168:171], v[96:111]
	s_waitcnt lgkmcnt(3)
	v_mfma_f32_32x32x16_bf16 v[112:127], v[238:241], v[164:167], v[112:127]
	s_waitcnt lgkmcnt(2)
	v_mfma_f32_32x32x16_bf16 v[96:111], v[242:245], v[164:167], v[96:111]
	s_waitcnt lgkmcnt(1)
	v_mfma_f32_32x32x16_bf16 v[112:127], v[246:249], v[160:163], v[112:127]
	s_waitcnt lgkmcnt(0)
	v_mfma_f32_32x32x16_bf16 v[96:111], v[2:5], v[160:163], v[96:111]
	s_setprio 0
	s_branch .LBB0_328

.LBB0_341:
	s_addk_i32 s57, 0x80
	s_cmp_le_i32 s57, s6
	s_cselect_b64 s[74:75], -1, 0
	s_cmp_gt_i32 s57, s6
	s_cbranch_scc1 .LBB0_346
	s_add_i32 s76, s69, 0
	v_add3_u32 v3, s76, v209, v208
	v_add3_u32 v8, s76, v210, v208
	v_add3_u32 v9, s76, v211, v208
	v_add3_u32 v10, s76, v212, v208
	s_setprio 1
	ds_read_b128 v[4:7], v3 offset:49152
	ds_read_b128 v[234:237], v3 offset:57344
	ds_read_b128 v[238:241], v8 offset:49152
	ds_read_b128 v[242:245], v8 offset:57344
	ds_read_b128 v[246:249], v9 offset:49152
	s_waitcnt lgkmcnt(4)
	v_mfma_f32_32x32x16_bf16 v[144:159], v[4:7], v[188:191], 0
	ds_read_b128 v[4:7], v9 offset:57344
	s_waitcnt lgkmcnt(4)
	v_mfma_f32_32x32x16_bf16 v[128:143], v[234:237], v[188:191], 0
	ds_read_b128 v[234:237], v10 offset:49152
	s_waitcnt lgkmcnt(4)
	v_mfma_f32_32x32x16_bf16 v[144:159], v[238:241], v[184:187], v[144:159]
	ds_read_b128 v[238:241], v10 offset:57344
	s_waitcnt lgkmcnt(4)
	v_mfma_f32_32x32x16_bf16 v[128:143], v[242:245], v[184:187], v[128:143]
	ds_read_b128 v[242:245], v3 offset:49280
	s_waitcnt lgkmcnt(4)
	v_mfma_f32_32x32x16_bf16 v[144:159], v[246:249], v[180:183], v[144:159]
	ds_read_b128 v[246:249], v3 offset:57472
	s_waitcnt lgkmcnt(4)
	v_mfma_f32_32x32x16_bf16 v[128:143], v[4:7], v[180:183], v[128:143]
	ds_read_b128 v[4:7], v8 offset:49280
	s_waitcnt lgkmcnt(4)
	v_mfma_f32_32x32x16_bf16 v[144:159], v[234:237], v[176:179], v[144:159]
	ds_read_b128 v[234:237], v8 offset:57472
	s_waitcnt lgkmcnt(4)
	v_mfma_f32_32x32x16_bf16 v[128:143], v[238:241], v[176:179], v[128:143]
	ds_read_b128 v[238:241], v9 offset:49280
	s_waitcnt lgkmcnt(4)
	v_mfma_f32_32x32x16_bf16 v[144:159], v[242:245], v[172:175], v[144:159]
	ds_read_b128 v[242:245], v9 offset:57472
	s_waitcnt lgkmcnt(4)
	v_mfma_f32_32x32x16_bf16 v[128:143], v[246:249], v[172:175], v[128:143]
	ds_read_b128 v[246:249], v10 offset:49280
	s_waitcnt lgkmcnt(4)
	v_mfma_f32_32x32x16_bf16 v[144:159], v[4:7], v[168:171], v[144:159]
	ds_read_b128 v[4:7], v10 offset:57472
	s_waitcnt lgkmcnt(4)
	v_mfma_f32_32x32x16_bf16 v[128:143], v[234:237], v[168:171], v[128:143]
	s_waitcnt lgkmcnt(3)
	v_mfma_f32_32x32x16_bf16 v[144:159], v[238:241], v[164:167], v[144:159]
	s_waitcnt lgkmcnt(2)
	v_mfma_f32_32x32x16_bf16 v[128:143], v[242:245], v[164:167], v[128:143]
	s_waitcnt lgkmcnt(1)
	v_mfma_f32_32x32x16_bf16 v[144:159], v[246:249], v[160:163], v[144:159]
	s_waitcnt lgkmcnt(0)
	v_mfma_f32_32x32x16_bf16 v[128:143], v[4:7], v[160:163], v[128:143]
	s_setprio 0
	s_branch .LBB0_347

.LBB0_1169:
	s_mov_b32 s61, s53
	s_mov_b32 s53, s65
	s_ashr_i32 s65, s64, 31
	s_lshl_b64 s[66:67], s[64:65], 14
	s_add_u32 s8, s54, s66
	s_addc_u32 s9, s55, s67
	s_add_i32 s70, s53, s90
	s_mov_b32 s71, m0
	s_mov_b32 m0, s70
	s_nop 0
	global_load_lds_dwordx4 v183, s[8:9]
	s_mov_b32 m0, s71
	s_addk_i32 s70, 0x400
	s_mov_b32 s71, m0
	s_mov_b32 m0, s70
	s_nop 0
	global_load_lds_dwordx4 v184, s[8:9]
	s_mov_b32 m0, s71
	s_lshl_b64 s[8:9], s[64:65], 8
	s_add_u32 s8, s58, s8
	s_addc_u32 s9, s59, s9
	s_ashr_i32 s65, s53, 6
	s_cmp_lg_u32 0, -1
	s_cselect_b32 s70, 0, 0
	s_add_i32 s65, s70, s65
	s_add_i32 s65, s65, 0x18800
	s_mov_b32 s70, m0
	s_mov_b32 m0, s65
	s_nop 0
	global_load_lds_dword v185, s[8:9]
	s_mov_b32 m0, s70
	s_add_i32 s8, s64, 1
	s_ashr_i32 s9, s8, 31
	s_lshl_b64 s[8:9], s[8:9], 14
	s_add_u32 s8, s56, s8
	s_addc_u32 s9, s57, s9
	s_add_i32 s65, s68, s83
	s_mov_b32 s70, m0
	s_mov_b32 m0, s65
	s_nop 0
	global_load_lds_dwordx4 v187, s[8:9]
	s_mov_b32 m0, s70
	s_addk_i32 s65, 0x400
	s_mov_b32 s70, m0
	s_mov_b32 m0, s65
	s_nop 0
	global_load_lds_dwordx4 v186, s[8:9]
	s_mov_b32 m0, s70
	s_ashr_i32 s8, s61, 8
	v_lshl_add_u32 v1, s8, 2, v128
	ds_read_b128 v[96:99], v1
	ds_read_b128 v[100:103], v1 offset:32
	ds_read_b128 v[80:83], v1 offset:128
	ds_read_b128 v[84:87], v1 offset:160
	ds_read_b128 v[104:107], v1 offset:64
	ds_read_b128 v[108:111], v1 offset:96
	ds_read_b128 v[88:91], v1 offset:192
	ds_read_b128 v[92:95], v1 offset:224
	s_add_i32 s8, s61, 0
	v_add3_u32 v1, s8, v197, v196
	v_add3_u32 v6, s8, v198, v196
	v_add3_u32 v7, s8, v199, v196
	v_add3_u32 v8, s8, v200, v196
	s_setprio 1
	ds_read_b128 v[2:5], v1 offset:49152
	ds_read_b128 v[220:223], v1 offset:57344
	ds_read_b128 v[224:227], v6 offset:49152
	ds_read_b128 v[228:231], v6 offset:57344
	ds_read_b128 v[232:235], v7 offset:49152
	s_waitcnt lgkmcnt(4)
	v_mfma_f32_32x32x16_bf16 v[96:111], v[2:5], v[172:175], v[96:111]
	ds_read_b128 v[2:5], v7 offset:57344
	s_waitcnt lgkmcnt(4)
	v_mfma_f32_32x32x16_bf16 v[80:95], v[220:223], v[172:175], v[80:95]
	ds_read_b128 v[220:223], v8 offset:49152
	s_waitcnt lgkmcnt(4)
	v_mfma_f32_32x32x16_bf16 v[96:111], v[224:227], v[168:171], v[96:111]
	ds_read_b128 v[224:227], v8 offset:57344
	s_waitcnt lgkmcnt(4)
	v_mfma_f32_32x32x16_bf16 v[80:95], v[228:231], v[168:171], v[80:95]
	ds_read_b128 v[228:231], v1 offset:49280
	s_waitcnt lgkmcnt(4)
	v_mfma_f32_32x32x16_bf16 v[96:111], v[232:235], v[164:167], v[96:111]
	ds_read_b128 v[232:235], v1 offset:57472
	s_waitcnt lgkmcnt(4)
	v_mfma_f32_32x32x16_bf16 v[80:95], v[2:5], v[164:167], v[80:95]
	ds_read_b128 v[2:5], v6 offset:49280
	s_waitcnt lgkmcnt(4)
	v_mfma_f32_32x32x16_bf16 v[96:111], v[220:223], v[160:163], v[96:111]
	ds_read_b128 v[220:223], v6 offset:57472
	s_waitcnt lgkmcnt(4)
	v_mfma_f32_32x32x16_bf16 v[80:95], v[224:227], v[160:163], v[80:95]
	ds_read_b128 v[224:227], v7 offset:49280
	s_waitcnt lgkmcnt(4)
	v_mfma_f32_32x32x16_bf16 v[96:111], v[228:231], v[156:159], v[96:111]
	ds_read_b128 v[228:231], v7 offset:57472
	s_waitcnt lgkmcnt(4)
	v_mfma_f32_32x32x16_bf16 v[80:95], v[232:235], v[156:159], v[80:95]
	ds_read_b128 v[232:235], v8 offset:49280
	s_waitcnt lgkmcnt(4)
	v_mfma_f32_32x32x16_bf16 v[96:111], v[2:5], v[152:155], v[96:111]
	ds_read_b128 v[2:5], v8 offset:57472
	s_waitcnt lgkmcnt(4)
	v_mfma_f32_32x32x16_bf16 v[80:95], v[220:223], v[152:155], v[80:95]
	s_waitcnt lgkmcnt(3)
	v_mfma_f32_32x32x16_bf16 v[96:111], v[224:227], v[148:151], v[96:111]
	s_waitcnt lgkmcnt(2)
	v_mfma_f32_32x32x16_bf16 v[80:95], v[228:231], v[148:151], v[80:95]
	s_waitcnt lgkmcnt(1)
	v_mfma_f32_32x32x16_bf16 v[96:111], v[232:235], v[144:147], v[96:111]
	s_waitcnt lgkmcnt(0)
	v_mfma_f32_32x32x16_bf16 v[80:95], v[2:5], v[144:147], v[80:95]
	s_setprio 0
	v_add_f32_e32 v1, 0, v215
	v_add_f32_e32 v1, v217, v1
	v_add_f32_e32 v1, v213, v1
	v_add_f32_e32 v1, v216, v1
	v_add_f32_e32 v1, v211, v1
	v_add_f32_e32 v1, v214, v1
	v_add_f32_e32 v1, v210, v1
	v_add_f32_e32 v1, v212, v1
	v_add_f32_e32 v1, v205, v1
	v_add_f32_e32 v1, v208, v1
	v_add_f32_e32 v1, v203, v1
	v_add_f32_e32 v1, v206, v1
	v_exp_f32_e32 v2, v126
	v_add_f32_e32 v1, v202, v1
	v_exp_f32_e32 v12, v127
	v_add_f32_e32 v1, v209, v1
	v_exp_f32_e32 v13, v124
	v_add_f32_e32 v1, v204, v1
	v_exp_f32_e32 v14, v125
	v_add_f32_e32 v1, v207, v1
	v_exp_f32_e32 v15, v122
	v_add_f32_e32 v1, v2, v1
	v_exp_f32_e32 v122, v123
	v_add_f32_e32 v1, v12, v1
	v_exp_f32_e32 v120, v120
	v_add_f32_e32 v1, v13, v1
	v_exp_f32_e32 v121, v121
	v_add_f32_e32 v1, v14, v1
	v_exp_f32_e32 v118, v118
	v_add_f32_e32 v1, v15, v1
	v_exp_f32_e32 v119, v119
	v_add_f32_e32 v1, v122, v1
	v_exp_f32_e32 v116, v116
	v_add_f32_e32 v1, v120, v1
	v_exp_f32_e32 v117, v117
	v_add_f32_e32 v1, v121, v1
	v_exp_f32_e32 v114, v114
	v_add_f32_e32 v1, v118, v1
	v_exp_f32_e32 v115, v115
	v_add_f32_e32 v1, v119, v1
	v_exp_f32_e32 v123, v112
	v_add_f32_e32 v1, v116, v1
	v_exp_f32_e32 v124, v113
	v_add_f32_e32 v1, v117, v1
	v_add_f32_e32 v1, v114, v1
	v_add_f32_e32 v1, v115, v1
	v_add_f32_e32 v1, v123, v1
	v_add_f32_e32 v1, v124, v1
	v_mov_b32_e32 v3, v1
	s_nop 1
	v_permlane32_swap_b32_e32 v1, v3
	v_cvt_pk_bf16_f32 v4, v215, v217
	v_cvt_pk_bf16_f32 v5, v213, v216
	v_cvt_pk_bf16_f32 v6, v211, v214
	v_cvt_pk_bf16_f32 v7, v210, v212
	v_cvt_pk_bf16_f32 v8, v205, v208
	v_cvt_pk_bf16_f32 v9, v203, v206
	v_cvt_pk_bf16_f32 v10, v202, v209
	v_cvt_pk_bf16_f32 v11, v204, v207
	v_cvt_pk_bf16_f32 v12, v2, v12
	v_cvt_pk_bf16_f32 v13, v13, v14
	v_cvt_pk_bf16_f32 v14, v15, v122
	v_cvt_pk_bf16_f32 v15, v120, v121
	v_cvt_pk_bf16_f32 v112, v118, v119
	v_cvt_pk_bf16_f32 v113, v116, v117
	v_cvt_pk_bf16_f32 v114, v114, v115
	v_cvt_pk_bf16_f32 v115, v123, v124
	s_nop 0
	v_permlane32_swap_b32_e32 v4, v6
	v_permlane32_swap_b32_e32 v5, v7
	v_permlane32_swap_b32_e32 v8, v10
	v_permlane32_swap_b32_e32 v9, v11
	v_permlane32_swap_b32_e32 v12, v14
	v_permlane32_swap_b32_e32 v13, v15
	v_permlane32_swap_b32_e32 v112, v114
	v_permlane32_swap_b32_e32 v113, v115
	v_add_u32_e32 v2, s53, v193
	ds_read_b64_tr_b16 v[116:117], v2 offset:0
	ds_read_b64_tr_b16 v[118:119], v2 offset:0x800
	ds_read_b64_tr_b16 v[120:121], v2 offset:0x1000
	ds_read_b64_tr_b16 v[122:123], v2 offset:0x1800
	ds_read_b64_tr_b16 v[124:125], v2 offset:0x2000
	ds_read_b64_tr_b16 v[126:127], v2 offset:0x2800
	ds_read_b64_tr_b16 v[132:133], v2 offset:0x3000
	ds_read_b64_tr_b16 v[134:135], v2 offset:0x3800
	s_waitcnt lgkmcnt(0)
	s_nop 0
	v_mfma_f32_32x32x16_bf16 v[16:31], v[4:7], v[116:119], v[16:31]
	ds_read_b64_tr_b16 v[116:117], v2 offset:0x200
	ds_read_b64_tr_b16 v[118:119], v2 offset:0xa00
	v_mfma_f32_32x32x16_bf16 v[16:31], v[8:11], v[120:123], v[16:31]
	ds_read_b64_tr_b16 v[120:121], v2 offset:0x1200
	ds_read_b64_tr_b16 v[122:123], v2 offset:0x1a00
	v_mfma_f32_32x32x16_bf16 v[16:31], v[12:15], v[124:127], v[16:31]
	ds_read_b64_tr_b16 v[124:125], v2 offset:0x2200
	ds_read_b64_tr_b16 v[126:127], v2 offset:0x2a00
	v_mfma_f32_32x32x16_bf16 v[16:31], v[112:115], v[132:135], v[16:31]
	ds_read_b64_tr_b16 v[132:133], v2 offset:0x3200
	ds_read_b64_tr_b16 v[134:135], v2 offset:0x3a00
	s_waitcnt lgkmcnt(0)
	v_mfma_f32_32x32x16_bf16 v[48:63], v[4:7], v[116:119], v[48:63]
	ds_read_b64_tr_b16 v[116:117], v2 offset:0x400
	ds_read_b64_tr_b16 v[118:119], v2 offset:0xc00
	v_mfma_f32_32x32x16_bf16 v[48:63], v[8:11], v[120:123], v[48:63]
	ds_read_b64_tr_b16 v[120:121], v2 offset:0x1400
	ds_read_b64_tr_b16 v[122:123], v2 offset:0x1c00
	v_mfma_f32_32x32x16_bf16 v[48:63], v[12:15], v[124:127], v[48:63]
	ds_read_b64_tr_b16 v[124:125], v2 offset:0x2400
	ds_read_b64_tr_b16 v[126:127], v2 offset:0x2c00
	v_mfma_f32_32x32x16_bf16 v[48:63], v[112:115], v[132:135], v[48:63]
	ds_read_b64_tr_b16 v[132:133], v2 offset:0x3400
	ds_read_b64_tr_b16 v[134:135], v2 offset:0x3c00
	s_waitcnt lgkmcnt(0)
	v_mfma_f32_32x32x16_bf16 v[64:79], v[4:7], v[116:119], v[64:79]
	ds_read_b64_tr_b16 v[116:117], v2 offset:0x600
	ds_read_b64_tr_b16 v[118:119], v2 offset:0xe00
	v_mfma_f32_32x32x16_bf16 v[64:79], v[8:11], v[120:123], v[64:79]
	ds_read_b64_tr_b16 v[120:121], v2 offset:0x1600
	ds_read_b64_tr_b16 v[122:123], v2 offset:0x1e00
	v_mfma_f32_32x32x16_bf16 v[64:79], v[12:15], v[124:127], v[64:79]
	ds_read_b64_tr_b16 v[124:125], v2 offset:0x2600
	ds_read_b64_tr_b16 v[126:127], v2 offset:0x2e00
	v_mfma_f32_32x32x16_bf16 v[64:79], v[112:115], v[132:135], v[64:79]
	ds_read_b64_tr_b16 v[132:133], v2 offset:0x3600
	ds_read_b64_tr_b16 v[134:135], v2 offset:0x3e00
	s_waitcnt lgkmcnt(0)
	v_mfma_f32_32x32x16_bf16 v[32:47], v[4:7], v[116:119], v[32:47]
	s_add_i32 s8, s91, 64
	s_cmp_le_i32 s8, s69
	v_mfma_f32_32x32x16_bf16 v[32:47], v[8:11], v[120:123], v[32:47]
	v_mfma_f32_32x32x16_bf16 v[32:47], v[12:15], v[124:127], v[32:47]
	v_mfma_f32_32x32x16_bf16 v[32:47], v[112:115], v[132:135], v[32:47]
	s_cbranch_scc1 .LBB0_1171
	v_add_u32_e32 v2, 0x4000003b, v130
	v_cmp_gt_u32_e32 vcc, 2.0, v2
	v_add_u32_e32 v2, 27, v130
	s_nop 0
	v_cndmask_b32_e32 v96, v179, v96, vcc
	v_cmp_lt_u32_e32 vcc, s96, v2
	v_add_u32_e32 v2, 58, v130
	s_nop 0
	v_cndmask_b32_e32 v80, v179, v80, vcc
	v_cmp_lt_u32_e32 vcc, s96, v2
	v_add_u32_e32 v2, 26, v130
	s_nop 0
	v_cndmask_b32_e32 v97, v179, v97, vcc
	v_cmp_lt_u32_e32 vcc, s96, v2
	v_add_u32_e32 v2, 57, v130
	s_nop 0
	v_cndmask_b32_e32 v81, v179, v81, vcc
	v_cmp_lt_u32_e32 vcc, s96, v2
	v_add_u32_e32 v2, 25, v130
	s_nop 0
	v_cndmask_b32_e32 v98, v179, v98, vcc
	v_cmp_lt_u32_e32 vcc, s96, v2
	v_add_u32_e32 v2, 56, v130
	s_nop 0
	v_cndmask_b32_e32 v82, v179, v82, vcc
	v_cmp_lt_u32_e32 vcc, s96, v2
	v_add_u32_e32 v2, 24, v130
	s_nop 0
	v_cndmask_b32_e32 v99, v179, v99, vcc
	v_cmp_lt_u32_e32 vcc, s96, v2
	v_add_u32_e32 v2, 51, v130
	s_nop 0
	v_cndmask_b32_e32 v83, v179, v83, vcc
	v_cmp_lt_u32_e32 vcc, s96, v2
	v_add_u32_e32 v2, 19, v130
	s_nop 0
	v_cndmask_b32_e32 v100, v179, v100, vcc
	v_cmp_lt_u32_e32 vcc, s96, v2
	v_add_u32_e32 v2, 50, v130
	s_nop 0
	v_cndmask_b32_e32 v84, v179, v84, vcc
	v_cmp_lt_u32_e32 vcc, s96, v2
	v_add_u32_e32 v2, 18, v130
	s_nop 0
	v_cndmask_b32_e32 v101, v179, v101, vcc
	v_cmp_lt_u32_e32 vcc, s96, v2
	v_add_u32_e32 v2, 49, v130
	s_nop 0
	v_cndmask_b32_e32 v85, v179, v85, vcc
	v_cmp_lt_u32_e32 vcc, s96, v2
	v_add_u32_e32 v2, 17, v130
	s_nop 0
	v_cndmask_b32_e32 v102, v179, v102, vcc
	v_cmp_lt_u32_e32 vcc, s96, v2
	v_add_u32_e32 v2, 48, v130
	s_nop 0
	v_cndmask_b32_e32 v86, v179, v86, vcc
	v_cmp_lt_u32_e32 vcc, s96, v2
	v_add_u32_e32 v2, 16, v130
	s_nop 0
	v_cndmask_b32_e32 v103, v179, v103, vcc
	v_cmp_lt_u32_e32 vcc, s96, v2
	v_add_u32_e32 v2, 43, v130
	s_nop 0
	v_cndmask_b32_e32 v87, v179, v87, vcc
	v_cmp_lt_u32_e32 vcc, s96, v2
	v_add_u32_e32 v2, 11, v130
	s_nop 0
	v_cndmask_b32_e32 v104, v179, v104, vcc
	v_cmp_lt_u32_e32 vcc, s96, v2
	v_add_u32_e32 v2, 42, v130
	s_nop 0
	v_cndmask_b32_e32 v88, v179, v88, vcc
	v_cmp_lt_u32_e32 vcc, s96, v2
	v_add_u32_e32 v2, 10, v130
	s_nop 0
	v_cndmask_b32_e32 v105, v179, v105, vcc
	v_cmp_lt_u32_e32 vcc, s96, v2
	v_add_u32_e32 v2, 41, v130
	s_nop 0
	v_cndmask_b32_e32 v89, v179, v89, vcc
	v_cmp_lt_u32_e32 vcc, s96, v2
	v_add_u32_e32 v2, 9, v130
	s_nop 0
	v_cndmask_b32_e32 v106, v179, v106, vcc
	v_cmp_lt_u32_e32 vcc, s96, v2
	v_add_u32_e32 v2, 40, v130
	s_nop 0
	v_cndmask_b32_e32 v90, v179, v90, vcc
	v_cmp_lt_u32_e32 vcc, s96, v2
	v_add_u32_e32 v2, 8, v130
	s_nop 0
	v_cndmask_b32_e32 v107, v179, v107, vcc
	v_cmp_lt_u32_e32 vcc, s96, v2
	v_add_u32_e32 v2, 35, v130
	s_nop 0
	v_cndmask_b32_e32 v91, v179, v91, vcc
	v_cmp_lt_u32_e32 vcc, s96, v2
	v_add_u32_e32 v2, 3, v130
	s_nop 0
	v_cndmask_b32_e32 v108, v179, v108, vcc
	v_cmp_lt_u32_e32 vcc, s96, v2
	v_add_u32_e32 v2, 34, v130
	s_nop 0
	v_cndmask_b32_e32 v92, v179, v92, vcc
	v_cmp_lt_u32_e32 vcc, s96, v2
	v_add_u32_e32 v2, 2, v130
	s_nop 0
	v_cndmask_b32_e32 v109, v179, v109, vcc
	v_cmp_lt_u32_e32 vcc, s96, v2
	v_add_u32_e32 v2, 33, v130
	s_nop 0
	v_cndmask_b32_e32 v93, v179, v93, vcc
	v_cmp_lt_u32_e32 vcc, s96, v2
	v_add_u32_e32 v2, 1, v130
	s_nop 0
	v_cndmask_b32_e32 v110, v179, v110, vcc
	v_cmp_lt_u32_e32 vcc, s96, v2
	v_add_u32_e32 v2, 32, v130
	s_nop 0
	v_cndmask_b32_e32 v94, v179, v94, vcc
	v_cmp_lt_u32_e32 vcc, s96, v2
	s_nop 1
	v_cndmask_b32_e32 v111, v179, v111, vcc
	v_cmp_lt_u32_e32 vcc, s96, v130
	s_nop 1
	v_cndmask_b32_e32 v95, v179, v95, vcc

.LBB0_1175:
	v_cndmask_b32_e64 v2, v2, v201, s[8:9]
	s_waitcnt vmcnt(5) lgkmcnt(0)
	s_barrier
	s_add_i32 s8, s61, s90
	s_mov_b32 s9, m0
	s_mov_b32 m0, s8
	s_nop 0
	global_load_lds_dwordx4 v183, s[62:63]
	s_mov_b32 m0, s9
	s_addk_i32 s8, 0x400
	s_mov_b32 s9, m0
	s_mov_b32 m0, s8
	s_nop 0
	global_load_lds_dwordx4 v184, s[62:63]
	s_mov_b32 m0, s9
	s_ashr_i32 s8, s61, 6
	s_cmp_lg_u32 0, -1
	s_cselect_b32 s9, 0, 0
	s_add_i32 s8, s9, s8
	s_add_i32 s8, s8, 0x18800
	s_mov_b32 s9, m0
	s_mov_b32 m0, s8
	s_nop 0
	global_load_lds_dword v185, s[0:1]
	s_mov_b32 m0, s9
	s_add_u32 s8, s56, s66
	s_addc_u32 s9, s57, s67
	s_add_i32 s65, s53, s83
	s_mov_b32 s66, m0
	s_mov_b32 m0, s65
	s_nop 0
	global_load_lds_dwordx4 v187, s[8:9]
	s_mov_b32 m0, s66
	s_addk_i32 s65, 0x400
	s_mov_b32 s66, m0
	s_mov_b32 m0, s65
	s_nop 0
	global_load_lds_dwordx4 v186, s[8:9]
	s_mov_b32 m0, s66
	v_mul_f32_e32 v5, 0xbe0293ee, v2
	v_fmamk_f32 v6, v96, 0x3e0293ee, v5
	v_fmamk_f32 v7, v97, 0x3e0293ee, v5
	v_fmamk_f32 v8, v98, 0x3e0293ee, v5
	v_fmamk_f32 v9, v99, 0x3e0293ee, v5
	v_fmamk_f32 v10, v100, 0x3e0293ee, v5
	v_fmamk_f32 v11, v101, 0x3e0293ee, v5
	v_fmamk_f32 v12, v102, 0x3e0293ee, v5
	v_fmamk_f32 v13, v103, 0x3e0293ee, v5
	v_fmamk_f32 v14, v104, 0x3e0293ee, v5
	v_fmamk_f32 v15, v105, 0x3e0293ee, v5
	v_fmamk_f32 v96, v106, 0x3e0293ee, v5
	v_fmamk_f32 v97, v107, 0x3e0293ee, v5
	v_fmamk_f32 v98, v108, 0x3e0293ee, v5
	v_fmamk_f32 v99, v109, 0x3e0293ee, v5
	v_fmamk_f32 v100, v110, 0x3e0293ee, v5
	v_fmamk_f32 v101, v111, 0x3e0293ee, v5
	v_fmamk_f32 v112, v80, 0x3e0293ee, v5
	v_fmamk_f32 v113, v81, 0x3e0293ee, v5
	v_fmamk_f32 v114, v82, 0x3e0293ee, v5
	v_fmamk_f32 v115, v83, 0x3e0293ee, v5
	v_fmamk_f32 v116, v84, 0x3e0293ee, v5
	v_fmamk_f32 v117, v85, 0x3e0293ee, v5
	v_fmamk_f32 v118, v86, 0x3e0293ee, v5
	v_fmamk_f32 v119, v87, 0x3e0293ee, v5
	v_fmamk_f32 v120, v88, 0x3e0293ee, v5
	v_fmamk_f32 v121, v89, 0x3e0293ee, v5
	v_fmamk_f32 v122, v90, 0x3e0293ee, v5
	v_fmamk_f32 v123, v91, 0x3e0293ee, v5
	v_fmamk_f32 v124, v92, 0x3e0293ee, v5
	v_fmamk_f32 v125, v93, 0x3e0293ee, v5
	v_fmamk_f32 v126, v94, 0x3e0293ee, v5
	v_fmac_f32_e32 v5, 0x3e0293ee, v95
	v_exp_f32_e32 v127, v6
	v_exp_f32_e32 v131, v7
	v_exp_f32_e32 v132, v8
	v_exp_f32_e32 v133, v9
	v_exp_f32_e32 v10, v10
	v_exp_f32_e32 v11, v11
	v_exp_f32_e32 v12, v12
	v_exp_f32_e32 v13, v13
	v_exp_f32_e32 v14, v14
	v_exp_f32_e32 v15, v15
	v_exp_f32_e32 v134, v96
	v_exp_f32_e32 v135, v97
	v_exp_f32_e32 v136, v98
	v_exp_f32_e32 v137, v99
	v_exp_f32_e32 v138, v100
	v_exp_f32_e32 v139, v101
	s_ashr_i32 s8, s68, 8
	v_lshl_add_u32 v6, s8, 2, v128
	ds_read_b128 v[96:99], v6
	ds_read_b128 v[100:103], v6 offset:32
	ds_read_b128 v[80:83], v6 offset:128
	ds_read_b128 v[84:87], v6 offset:160
	ds_read_b128 v[104:107], v6 offset:64
	ds_read_b128 v[108:111], v6 offset:96
	ds_read_b128 v[88:91], v6 offset:192
	ds_read_b128 v[92:95], v6 offset:224
	s_add_i32 s8, s68, 0
	v_add3_u32 v140, s8, v197, v196
	v_add3_u32 v141, s8, v198, v196
	v_add3_u32 v142, s8, v199, v196
	v_add3_u32 v143, s8, v200, v196
	s_setprio 1
	ds_read_b128 v[6:9], v140 offset:49152
	ds_read_b128 v[220:223], v140 offset:57344
	ds_read_b128 v[224:227], v141 offset:49152
	ds_read_b128 v[228:231], v141 offset:57344
	ds_read_b128 v[232:235], v142 offset:49152
	s_waitcnt lgkmcnt(4)
	v_mfma_f32_32x32x16_bf16 v[96:111], v[6:9], v[172:175], v[96:111]
	ds_read_b128 v[6:9], v142 offset:57344
	s_waitcnt lgkmcnt(4)
	v_mfma_f32_32x32x16_bf16 v[80:95], v[220:223], v[172:175], v[80:95]
	ds_read_b128 v[220:223], v143 offset:49152
	s_waitcnt lgkmcnt(4)
	v_mfma_f32_32x32x16_bf16 v[96:111], v[224:227], v[168:171], v[96:111]
	ds_read_b128 v[224:227], v143 offset:57344
	s_waitcnt lgkmcnt(4)
	v_mfma_f32_32x32x16_bf16 v[80:95], v[228:231], v[168:171], v[80:95]
	ds_read_b128 v[228:231], v140 offset:49280
	s_waitcnt lgkmcnt(4)
	v_mfma_f32_32x32x16_bf16 v[96:111], v[232:235], v[164:167], v[96:111]
	ds_read_b128 v[232:235], v140 offset:57472
	s_waitcnt lgkmcnt(4)
	v_mfma_f32_32x32x16_bf16 v[80:95], v[6:9], v[164:167], v[80:95]
	ds_read_b128 v[6:9], v141 offset:49280
	s_waitcnt lgkmcnt(4)
	v_mfma_f32_32x32x16_bf16 v[96:111], v[220:223], v[160:163], v[96:111]
	ds_read_b128 v[220:223], v141 offset:57472
	s_waitcnt lgkmcnt(4)
	v_mfma_f32_32x32x16_bf16 v[80:95], v[224:227], v[160:163], v[80:95]
	ds_read_b128 v[224:227], v142 offset:49280
	s_waitcnt lgkmcnt(4)
	v_mfma_f32_32x32x16_bf16 v[96:111], v[228:231], v[156:159], v[96:111]
	ds_read_b128 v[228:231], v142 offset:57472
	s_waitcnt lgkmcnt(4)
	v_mfma_f32_32x32x16_bf16 v[80:95], v[232:235], v[156:159], v[80:95]
	ds_read_b128 v[232:235], v143 offset:49280
	s_waitcnt lgkmcnt(4)
	v_mfma_f32_32x32x16_bf16 v[96:111], v[6:9], v[152:155], v[96:111]
	ds_read_b128 v[6:9], v143 offset:57472
	s_waitcnt lgkmcnt(4)
	v_mfma_f32_32x32x16_bf16 v[80:95], v[220:223], v[152:155], v[80:95]
	s_waitcnt lgkmcnt(3)
	v_mfma_f32_32x32x16_bf16 v[96:111], v[224:227], v[148:151], v[96:111]
	s_waitcnt lgkmcnt(2)
	v_mfma_f32_32x32x16_bf16 v[80:95], v[228:231], v[148:151], v[80:95]
	s_waitcnt lgkmcnt(1)
	v_mfma_f32_32x32x16_bf16 v[96:111], v[232:235], v[144:147], v[96:111]
	s_waitcnt lgkmcnt(0)
	v_mfma_f32_32x32x16_bf16 v[80:95], v[6:9], v[144:147], v[80:95]
	s_setprio 0
	v_exp_f32_e32 v7, v112
	v_exp_f32_e32 v112, v113
	v_exp_f32_e32 v113, v114
	v_exp_f32_e32 v114, v115
	v_exp_f32_e32 v115, v116
	v_exp_f32_e32 v116, v117
	v_exp_f32_e32 v117, v118
	v_exp_f32_e32 v118, v119
	v_exp_f32_e32 v119, v120
	v_exp_f32_e32 v120, v121
	v_exp_f32_e32 v121, v122
	v_exp_f32_e32 v122, v123
	v_exp_f32_e32 v123, v124
	v_exp_f32_e32 v124, v125
	v_exp_f32_e32 v125, v126
	v_exp_f32_e32 v126, v5
	v_add_f32_e32 v5, 0, v127
	v_add_f32_e32 v5, v131, v5
	v_add_f32_e32 v5, v132, v5
	v_add_f32_e32 v5, v133, v5
	v_add_f32_e32 v5, v10, v5
	v_add_f32_e32 v5, v11, v5
	v_add_f32_e32 v5, v12, v5
	v_add_f32_e32 v5, v13, v5
	v_add_f32_e32 v5, v14, v5
	v_add_f32_e32 v5, v15, v5
	v_add_f32_e32 v5, v134, v5
	v_add_f32_e32 v5, v135, v5
	v_add_f32_e32 v5, v136, v5
	v_add_f32_e32 v5, v137, v5
	v_add_f32_e32 v5, v138, v5
	v_add_f32_e32 v5, v139, v5
	v_add_f32_e32 v5, v7, v5
	v_add_f32_e32 v5, v112, v5
	v_add_f32_e32 v5, v113, v5
	v_add_f32_e32 v5, v114, v5
	v_add_f32_e32 v5, v115, v5
	v_add_f32_e32 v5, v116, v5
	v_add_f32_e32 v5, v117, v5
	v_add_f32_e32 v5, v118, v5
	v_add_f32_e32 v5, v119, v5
	v_add_f32_e32 v5, v120, v5
	v_add_f32_e32 v5, v121, v5
	v_add_f32_e32 v5, v122, v5
	v_add_f32_e32 v5, v123, v5
	v_add_f32_e32 v5, v124, v5
	v_add_f32_e32 v5, v125, v5
	v_add_f32_e32 v5, v126, v5
	v_mov_b32_e32 v6, v5
	s_nop 1
	v_permlane32_swap_b32_e32 v5, v6
	v_cvt_pk_bf16_f32 v8, v127, v131
	v_cvt_pk_bf16_f32 v9, v132, v133
	v_cvt_pk_bf16_f32 v10, v10, v11
	v_cvt_pk_bf16_f32 v11, v12, v13
	v_cvt_pk_bf16_f32 v12, v14, v15
	v_cvt_pk_bf16_f32 v13, v134, v135
	v_cvt_pk_bf16_f32 v14, v136, v137
	v_cvt_pk_bf16_f32 v15, v138, v139
	v_cvt_pk_bf16_f32 v112, v7, v112
	v_cvt_pk_bf16_f32 v113, v113, v114
	v_cvt_pk_bf16_f32 v114, v115, v116
	v_cvt_pk_bf16_f32 v115, v117, v118
	v_cvt_pk_bf16_f32 v116, v119, v120
	v_cvt_pk_bf16_f32 v117, v121, v122
	v_cvt_pk_bf16_f32 v118, v123, v124
	v_cvt_pk_bf16_f32 v119, v125, v126
	s_nop 0
	v_permlane32_swap_b32_e32 v8, v10
	v_permlane32_swap_b32_e32 v9, v11
	v_permlane32_swap_b32_e32 v12, v14
	v_permlane32_swap_b32_e32 v13, v15
	v_permlane32_swap_b32_e32 v112, v114
	v_permlane32_swap_b32_e32 v113, v115
	v_permlane32_swap_b32_e32 v116, v118
	v_permlane32_swap_b32_e32 v117, v119
	v_add_u32_e32 v7, s61, v193
	ds_read_b64_tr_b16 v[120:121], v7 offset:0
	ds_read_b64_tr_b16 v[122:123], v7 offset:0x800
	ds_read_b64_tr_b16 v[124:125], v7 offset:0x1000
	ds_read_b64_tr_b16 v[126:127], v7 offset:0x1800
	ds_read_b64_tr_b16 v[132:133], v7 offset:0x2000
	ds_read_b64_tr_b16 v[134:135], v7 offset:0x2800
	ds_read_b64_tr_b16 v[136:137], v7 offset:0x3000
	ds_read_b64_tr_b16 v[138:139], v7 offset:0x3800
	s_waitcnt lgkmcnt(0)
	s_nop 0
	v_mfma_f32_32x32x16_bf16 v[16:31], v[8:11], v[120:123], v[16:31]
	ds_read_b64_tr_b16 v[120:121], v7 offset:0x200
	ds_read_b64_tr_b16 v[122:123], v7 offset:0xa00
	v_mfma_f32_32x32x16_bf16 v[16:31], v[12:15], v[124:127], v[16:31]
	ds_read_b64_tr_b16 v[124:125], v7 offset:0x1200
	ds_read_b64_tr_b16 v[126:127], v7 offset:0x1a00
	v_mfma_f32_32x32x16_bf16 v[16:31], v[112:115], v[132:135], v[16:31]
	ds_read_b64_tr_b16 v[132:133], v7 offset:0x2200
	ds_read_b64_tr_b16 v[134:135], v7 offset:0x2a00
	v_mfma_f32_32x32x16_bf16 v[16:31], v[116:119], v[136:139], v[16:31]
	ds_read_b64_tr_b16 v[136:137], v7 offset:0x3200
	ds_read_b64_tr_b16 v[138:139], v7 offset:0x3a00
	s_waitcnt lgkmcnt(0)
	v_mfma_f32_32x32x16_bf16 v[48:63], v[8:11], v[120:123], v[48:63]
	ds_read_b64_tr_b16 v[120:121], v7 offset:0x400
	ds_read_b64_tr_b16 v[122:123], v7 offset:0xc00
	v_mfma_f32_32x32x16_bf16 v[48:63], v[12:15], v[124:127], v[48:63]
	ds_read_b64_tr_b16 v[124:125], v7 offset:0x1400
	ds_read_b64_tr_b16 v[126:127], v7 offset:0x1c00
	v_mfma_f32_32x32x16_bf16 v[48:63], v[112:115], v[132:135], v[48:63]
	ds_read_b64_tr_b16 v[132:133], v7 offset:0x2400
	ds_read_b64_tr_b16 v[134:135], v7 offset:0x2c00
	v_mfma_f32_32x32x16_bf16 v[48:63], v[116:119], v[136:139], v[48:63]
	ds_read_b64_tr_b16 v[136:137], v7 offset:0x3400
	ds_read_b64_tr_b16 v[138:139], v7 offset:0x3c00
	s_waitcnt lgkmcnt(0)
	v_mfma_f32_32x32x16_bf16 v[64:79], v[8:11], v[120:123], v[64:79]
	ds_read_b64_tr_b16 v[120:121], v7 offset:0x600
	ds_read_b64_tr_b16 v[122:123], v7 offset:0xe00
	v_mfma_f32_32x32x16_bf16 v[64:79], v[12:15], v[124:127], v[64:79]
	ds_read_b64_tr_b16 v[124:125], v7 offset:0x1600
	ds_read_b64_tr_b16 v[126:127], v7 offset:0x1e00
	v_mfma_f32_32x32x16_bf16 v[64:79], v[112:115], v[132:135], v[64:79]
	ds_read_b64_tr_b16 v[132:133], v7 offset:0x2600
	ds_read_b64_tr_b16 v[134:135], v7 offset:0x2e00
	v_mfma_f32_32x32x16_bf16 v[64:79], v[116:119], v[136:139], v[64:79]
	ds_read_b64_tr_b16 v[136:137], v7 offset:0x3600
	ds_read_b64_tr_b16 v[138:139], v7 offset:0x3e00
	s_waitcnt lgkmcnt(0)
	v_mfma_f32_32x32x16_bf16 v[32:47], v[8:11], v[120:123], v[32:47]
	s_cmp_le_i32 s91, s69
	v_mfma_f32_32x32x16_bf16 v[32:47], v[12:15], v[124:127], v[32:47]
	v_mfma_f32_32x32x16_bf16 v[32:47], v[112:115], v[132:135], v[32:47]
	v_mfma_f32_32x32x16_bf16 v[32:47], v[116:119], v[136:139], v[32:47]
	s_cbranch_scc1 .LBB0_1177
	v_add_u32_e32 v7, 0x4000007b, v130
	v_cmp_gt_u32_e32 vcc, 2.0, v7
	v_add_u32_e32 v7, 0x5b, v130
	s_nop 0
	v_cndmask_b32_e32 v96, v179, v96, vcc
	v_cmp_lt_u32_e32 vcc, s96, v7
	v_add_u32_e32 v7, 0x7a, v130
	s_nop 0
	v_cndmask_b32_e32 v80, v179, v80, vcc
	v_cmp_lt_u32_e32 vcc, s96, v7
	v_add_u32_e32 v7, 0x5a, v130
	s_nop 0
	v_cndmask_b32_e32 v97, v179, v97, vcc
	v_cmp_lt_u32_e32 vcc, s96, v7
	v_add_u32_e32 v7, 0x79, v130
	s_nop 0
	v_cndmask_b32_e32 v81, v179, v81, vcc
	v_cmp_lt_u32_e32 vcc, s96, v7
	v_add_u32_e32 v7, 0x59, v130
	s_nop 0
	v_cndmask_b32_e32 v98, v179, v98, vcc
	v_cmp_lt_u32_e32 vcc, s96, v7
	v_add_u32_e32 v7, 0x78, v130
	s_nop 0
	v_cndmask_b32_e32 v82, v179, v82, vcc
	v_cmp_lt_u32_e32 vcc, s96, v7
	v_add_u32_e32 v7, 0x58, v130
	s_nop 0
	v_cndmask_b32_e32 v99, v179, v99, vcc
	v_cmp_lt_u32_e32 vcc, s96, v7
	v_add_u32_e32 v7, 0x73, v130
	s_nop 0
	v_cndmask_b32_e32 v83, v179, v83, vcc
	v_cmp_lt_u32_e32 vcc, s96, v7
	v_add_u32_e32 v7, 0x53, v130
	s_nop 0
	v_cndmask_b32_e32 v100, v179, v100, vcc
	v_cmp_lt_u32_e32 vcc, s96, v7
	v_add_u32_e32 v7, 0x72, v130
	s_nop 0
	v_cndmask_b32_e32 v84, v179, v84, vcc
	v_cmp_lt_u32_e32 vcc, s96, v7
	v_add_u32_e32 v7, 0x52, v130
	s_nop 0
	v_cndmask_b32_e32 v101, v179, v101, vcc
	v_cmp_lt_u32_e32 vcc, s96, v7
	v_add_u32_e32 v7, 0x71, v130
	s_nop 0
	v_cndmask_b32_e32 v85, v179, v85, vcc
	v_cmp_lt_u32_e32 vcc, s96, v7
	v_add_u32_e32 v7, 0x51, v130
	s_nop 0
	v_cndmask_b32_e32 v102, v179, v102, vcc
	v_cmp_lt_u32_e32 vcc, s96, v7
	v_add_u32_e32 v7, 0x70, v130
	s_nop 0
	v_cndmask_b32_e32 v86, v179, v86, vcc
	v_cmp_lt_u32_e32 vcc, s96, v7
	v_add_u32_e32 v7, 0x50, v130
	s_nop 0
	v_cndmask_b32_e32 v103, v179, v103, vcc
	v_cmp_lt_u32_e32 vcc, s96, v7
	v_add_u32_e32 v7, 0x6b, v130
	s_nop 0
	v_cndmask_b32_e32 v87, v179, v87, vcc
	v_cmp_lt_u32_e32 vcc, s96, v7
	v_add_u32_e32 v7, 0x4b, v130
	s_nop 0
	v_cndmask_b32_e32 v104, v179, v104, vcc
	v_cmp_lt_u32_e32 vcc, s96, v7
	v_add_u32_e32 v7, 0x6a, v130
	s_nop 0
	v_cndmask_b32_e32 v88, v179, v88, vcc
	v_cmp_lt_u32_e32 vcc, s96, v7
	v_add_u32_e32 v7, 0x4a, v130
	s_nop 0
	v_cndmask_b32_e32 v105, v179, v105, vcc
	v_cmp_lt_u32_e32 vcc, s96, v7
	v_add_u32_e32 v7, 0x69, v130
	s_nop 0
	v_cndmask_b32_e32 v89, v179, v89, vcc
	v_cmp_lt_u32_e32 vcc, s96, v7
	v_add_u32_e32 v7, 0x49, v130
	s_nop 0
	v_cndmask_b32_e32 v106, v179, v106, vcc
	v_cmp_lt_u32_e32 vcc, s96, v7
	v_add_u32_e32 v7, 0x68, v130
	s_nop 0
	v_cndmask_b32_e32 v90, v179, v90, vcc
	v_cmp_lt_u32_e32 vcc, s96, v7
	v_add_u32_e32 v7, 0x48, v130
	s_nop 0
	v_cndmask_b32_e32 v107, v179, v107, vcc
	v_cmp_lt_u32_e32 vcc, s96, v7
	v_add_u32_e32 v7, 0x63, v130
	s_nop 0
	v_cndmask_b32_e32 v91, v179, v91, vcc
	v_cmp_lt_u32_e32 vcc, s96, v7
	v_add_u32_e32 v7, 0x43, v130
	s_nop 0
	v_cndmask_b32_e32 v108, v179, v108, vcc
	v_cmp_lt_u32_e32 vcc, s96, v7
	v_add_u32_e32 v7, 0x62, v130
	s_nop 0
	v_cndmask_b32_e32 v92, v179, v92, vcc
	v_cmp_lt_u32_e32 vcc, s96, v7
	v_add_u32_e32 v7, 0x42, v130
	s_nop 0
	v_cndmask_b32_e32 v109, v179, v109, vcc
	v_cmp_lt_u32_e32 vcc, s96, v7
	v_add_u32_e32 v7, 0x61, v130
	s_nop 0
	v_cndmask_b32_e32 v93, v179, v93, vcc
	v_cmp_lt_u32_e32 vcc, s96, v7
	v_add_u32_e32 v7, 0x41, v130
	s_nop 0
	v_cndmask_b32_e32 v110, v179, v110, vcc
	v_cmp_lt_u32_e32 vcc, s96, v7
	v_add_u32_e32 v7, 0x60, v130
	s_nop 0
	v_cndmask_b32_e32 v94, v179, v94, vcc
	v_cmp_lt_u32_e32 vcc, s96, v7
	v_add_u32_e32 v7, 64, v130
	s_nop 0
	v_cndmask_b32_e32 v111, v179, v111, vcc
	v_cmp_lt_u32_e32 vcc, s96, v7
	s_nop 1
	v_cndmask_b32_e32 v95, v179, v95, vcc

.LBB0_1189:
	s_add_i32 s8, s0, 2
	s_ashr_i32 s9, s8, 31
	s_lshl_b64 s[8:9], s[8:9], 14
	s_add_u32 s8, s56, s8
	s_addc_u32 s9, s57, s9
	s_add_i32 s1, s68, s83
	s_mov_b32 s64, m0
	s_mov_b32 m0, s1
	s_nop 0
	global_load_lds_dwordx4 v187, s[8:9]
	s_mov_b32 m0, s64
	s_addk_i32 s1, 0x400
	s_mov_b32 s64, m0
	s_mov_b32 m0, s1
	s_nop 0
	global_load_lds_dwordx4 v186, s[8:9]
	s_mov_b32 m0, s64
	s_ashr_i32 s1, s66, 8
	v_lshl_add_u32 v2, s1, 2, v128
	ds_read_b128 v[96:99], v2
	ds_read_b128 v[100:103], v2 offset:32
	ds_read_b128 v[80:83], v2 offset:128
	ds_read_b128 v[84:87], v2 offset:160
	ds_read_b128 v[104:107], v2 offset:64
	ds_read_b128 v[108:111], v2 offset:96
	ds_read_b128 v[88:91], v2 offset:192
	ds_read_b128 v[92:95], v2 offset:224
	s_add_i32 s1, s66, 0
	v_add3_u32 v6, s1, v197, v196
	v_add3_u32 v7, s1, v198, v196
	v_add3_u32 v8, s1, v199, v196
	v_add3_u32 v9, s1, v200, v196
	s_setprio 1
	ds_read_b128 v[2:5], v6 offset:49152
	ds_read_b128 v[220:223], v6 offset:57344
	ds_read_b128 v[224:227], v7 offset:49152
	ds_read_b128 v[228:231], v7 offset:57344
	ds_read_b128 v[232:235], v8 offset:49152
	s_waitcnt lgkmcnt(4)
	v_mfma_f32_32x32x16_bf16 v[96:111], v[2:5], v[172:175], v[96:111]
	ds_read_b128 v[2:5], v8 offset:57344
	s_waitcnt lgkmcnt(4)
	v_mfma_f32_32x32x16_bf16 v[80:95], v[220:223], v[172:175], v[80:95]
	ds_read_b128 v[220:223], v9 offset:49152
	s_waitcnt lgkmcnt(4)
	v_mfma_f32_32x32x16_bf16 v[96:111], v[224:227], v[168:171], v[96:111]
	ds_read_b128 v[224:227], v9 offset:57344
	s_waitcnt lgkmcnt(4)
	v_mfma_f32_32x32x16_bf16 v[80:95], v[228:231], v[168:171], v[80:95]
	ds_read_b128 v[228:231], v6 offset:49280
	s_waitcnt lgkmcnt(4)
	v_mfma_f32_32x32x16_bf16 v[96:111], v[232:235], v[164:167], v[96:111]
	ds_read_b128 v[232:235], v6 offset:57472
	s_waitcnt lgkmcnt(4)
	v_mfma_f32_32x32x16_bf16 v[80:95], v[2:5], v[164:167], v[80:95]
	ds_read_b128 v[2:5], v7 offset:49280
	s_waitcnt lgkmcnt(4)
	v_mfma_f32_32x32x16_bf16 v[96:111], v[220:223], v[160:163], v[96:111]
	ds_read_b128 v[220:223], v7 offset:57472
	s_waitcnt lgkmcnt(4)
	v_mfma_f32_32x32x16_bf16 v[80:95], v[224:227], v[160:163], v[80:95]
	ds_read_b128 v[224:227], v8 offset:49280
	s_waitcnt lgkmcnt(4)
	v_mfma_f32_32x32x16_bf16 v[96:111], v[228:231], v[156:159], v[96:111]
	ds_read_b128 v[228:231], v8 offset:57472
	s_waitcnt lgkmcnt(4)
	v_mfma_f32_32x32x16_bf16 v[80:95], v[232:235], v[156:159], v[80:95]
	ds_read_b128 v[232:235], v9 offset:49280
	s_waitcnt lgkmcnt(4)
	v_mfma_f32_32x32x16_bf16 v[96:111], v[2:5], v[152:155], v[96:111]
	ds_read_b128 v[2:5], v9 offset:57472
	s_waitcnt lgkmcnt(4)
	v_mfma_f32_32x32x16_bf16 v[80:95], v[220:223], v[152:155], v[80:95]
	s_waitcnt lgkmcnt(3)
	v_mfma_f32_32x32x16_bf16 v[96:111], v[224:227], v[148:151], v[96:111]
	s_waitcnt lgkmcnt(2)
	v_mfma_f32_32x32x16_bf16 v[80:95], v[228:231], v[148:151], v[80:95]
	s_waitcnt lgkmcnt(1)
	v_mfma_f32_32x32x16_bf16 v[96:111], v[232:235], v[144:147], v[96:111]
	s_waitcnt lgkmcnt(0)
	v_mfma_f32_32x32x16_bf16 v[80:95], v[2:5], v[144:147], v[80:95]
	s_setprio 0
	v_add_f32_e32 v3, 0, v215
	v_add_f32_e32 v3, v217, v3
	v_add_f32_e32 v3, v213, v3
	v_add_f32_e32 v3, v216, v3
	v_add_f32_e32 v3, v211, v3
	v_add_f32_e32 v3, v214, v3
	v_add_f32_e32 v3, v210, v3
	v_add_f32_e32 v3, v212, v3
	v_add_f32_e32 v3, v205, v3
	v_add_f32_e32 v3, v208, v3
	v_add_f32_e32 v3, v203, v3
	v_add_f32_e32 v3, v206, v3
	v_exp_f32_e32 v2, v126
	v_add_f32_e32 v3, v202, v3
	v_exp_f32_e32 v5, v127
	v_add_f32_e32 v3, v209, v3
	v_exp_f32_e32 v14, v124
	v_add_f32_e32 v3, v204, v3
	v_exp_f32_e32 v15, v125
	v_add_f32_e32 v3, v207, v3
	v_exp_f32_e32 v122, v122
	v_add_f32_e32 v3, v2, v3
	v_exp_f32_e32 v123, v123
	v_add_f32_e32 v3, v5, v3
	v_exp_f32_e32 v120, v120
	v_add_f32_e32 v3, v14, v3
	v_exp_f32_e32 v121, v121
	v_add_f32_e32 v3, v15, v3
	v_exp_f32_e32 v118, v118
	v_add_f32_e32 v3, v122, v3
	v_exp_f32_e32 v119, v119
	v_add_f32_e32 v3, v123, v3
	v_exp_f32_e32 v124, v116
	v_add_f32_e32 v3, v120, v3
	v_exp_f32_e32 v117, v117
	v_add_f32_e32 v3, v121, v3
	v_exp_f32_e32 v125, v114
	v_add_f32_e32 v3, v118, v3
	v_exp_f32_e32 v126, v115
	v_add_f32_e32 v3, v119, v3
	v_exp_f32_e32 v127, v112
	v_add_f32_e32 v3, v124, v3
	v_exp_f32_e32 v130, v113
	v_add_f32_e32 v3, v117, v3
	v_add_f32_e32 v3, v125, v3
	v_add_f32_e32 v3, v126, v3
	v_add_f32_e32 v3, v127, v3
	v_add_f32_e32 v3, v130, v3
	v_mov_b32_e32 v4, v3
	s_nop 1
	v_permlane32_swap_b32_e32 v3, v4
	v_cvt_pk_bf16_f32 v6, v215, v217
	v_cvt_pk_bf16_f32 v7, v213, v216
	v_cvt_pk_bf16_f32 v8, v211, v214
	v_cvt_pk_bf16_f32 v9, v210, v212
	v_cvt_pk_bf16_f32 v10, v205, v208
	v_cvt_pk_bf16_f32 v11, v203, v206
	v_cvt_pk_bf16_f32 v12, v202, v209
	v_cvt_pk_bf16_f32 v13, v204, v207
	v_cvt_pk_bf16_f32 v112, v2, v5
	v_cvt_pk_bf16_f32 v113, v14, v15
	v_cvt_pk_bf16_f32 v114, v122, v123
	v_cvt_pk_bf16_f32 v115, v120, v121
	v_cvt_pk_bf16_f32 v116, v118, v119
	v_cvt_pk_bf16_f32 v117, v124, v117
	v_cvt_pk_bf16_f32 v118, v125, v126
	v_cvt_pk_bf16_f32 v119, v127, v130
	s_nop 0
	v_permlane32_swap_b32_e32 v6, v8
	v_permlane32_swap_b32_e32 v7, v9
	v_permlane32_swap_b32_e32 v10, v12
	v_permlane32_swap_b32_e32 v11, v13
	v_permlane32_swap_b32_e32 v112, v114
	v_permlane32_swap_b32_e32 v113, v115
	v_permlane32_swap_b32_e32 v116, v118
	v_permlane32_swap_b32_e32 v117, v119
	v_add_u32_e32 v2, s53, v193
	ds_read_b64_tr_b16 v[120:121], v2 offset:0
	ds_read_b64_tr_b16 v[122:123], v2 offset:0x800
	ds_read_b64_tr_b16 v[124:125], v2 offset:0x1000
	ds_read_b64_tr_b16 v[126:127], v2 offset:0x1800
	ds_read_b64_tr_b16 v[130:131], v2 offset:0x2000
	ds_read_b64_tr_b16 v[132:133], v2 offset:0x2800
	ds_read_b64_tr_b16 v[134:135], v2 offset:0x3000
	ds_read_b64_tr_b16 v[136:137], v2 offset:0x3800
	s_waitcnt lgkmcnt(0)
	s_nop 0
	v_mfma_f32_32x32x16_bf16 v[16:31], v[6:9], v[120:123], v[16:31]
	ds_read_b64_tr_b16 v[120:121], v2 offset:0x200
	ds_read_b64_tr_b16 v[122:123], v2 offset:0xa00
	v_mfma_f32_32x32x16_bf16 v[16:31], v[10:13], v[124:127], v[16:31]
	ds_read_b64_tr_b16 v[124:125], v2 offset:0x1200
	ds_read_b64_tr_b16 v[126:127], v2 offset:0x1a00
	v_mfma_f32_32x32x16_bf16 v[16:31], v[112:115], v[130:133], v[16:31]
	ds_read_b64_tr_b16 v[130:131], v2 offset:0x2200
	ds_read_b64_tr_b16 v[132:133], v2 offset:0x2a00
	v_mfma_f32_32x32x16_bf16 v[16:31], v[116:119], v[134:137], v[16:31]
	ds_read_b64_tr_b16 v[134:135], v2 offset:0x3200
	ds_read_b64_tr_b16 v[136:137], v2 offset:0x3a00
	s_waitcnt lgkmcnt(0)
	v_mfma_f32_32x32x16_bf16 v[48:63], v[6:9], v[120:123], v[48:63]
	ds_read_b64_tr_b16 v[120:121], v2 offset:0x400
	ds_read_b64_tr_b16 v[122:123], v2 offset:0xc00
	v_mfma_f32_32x32x16_bf16 v[48:63], v[10:13], v[124:127], v[48:63]
	ds_read_b64_tr_b16 v[124:125], v2 offset:0x1400
	ds_read_b64_tr_b16 v[126:127], v2 offset:0x1c00
	v_mfma_f32_32x32x16_bf16 v[48:63], v[112:115], v[130:133], v[48:63]
	ds_read_b64_tr_b16 v[130:131], v2 offset:0x2400
	ds_read_b64_tr_b16 v[132:133], v2 offset:0x2c00
	v_mfma_f32_32x32x16_bf16 v[48:63], v[116:119], v[134:137], v[48:63]
	ds_read_b64_tr_b16 v[134:135], v2 offset:0x3400
	ds_read_b64_tr_b16 v[136:137], v2 offset:0x3c00
	s_waitcnt lgkmcnt(0)
	v_mfma_f32_32x32x16_bf16 v[64:79], v[6:9], v[120:123], v[64:79]
	ds_read_b64_tr_b16 v[120:121], v2 offset:0x600
	ds_read_b64_tr_b16 v[122:123], v2 offset:0xe00
	v_mfma_f32_32x32x16_bf16 v[64:79], v[10:13], v[124:127], v[64:79]
	ds_read_b64_tr_b16 v[124:125], v2 offset:0x1600
	ds_read_b64_tr_b16 v[126:127], v2 offset:0x1e00
	v_mfma_f32_32x32x16_bf16 v[64:79], v[112:115], v[130:133], v[64:79]
	ds_read_b64_tr_b16 v[130:131], v2 offset:0x2600
	ds_read_b64_tr_b16 v[132:133], v2 offset:0x2e00
	v_mfma_f32_32x32x16_bf16 v[64:79], v[116:119], v[134:137], v[64:79]
	ds_read_b64_tr_b16 v[134:135], v2 offset:0x3600
	ds_read_b64_tr_b16 v[136:137], v2 offset:0x3e00
	s_waitcnt lgkmcnt(0)
	v_mfma_f32_32x32x16_bf16 v[32:47], v[6:9], v[120:123], v[32:47]
	s_add_i32 s1, s70, 64
	s_cmp_le_i32 s1, s69
	v_mfma_f32_32x32x16_bf16 v[32:47], v[10:13], v[124:127], v[32:47]
	v_mfma_f32_32x32x16_bf16 v[32:47], v[112:115], v[130:133], v[32:47]
	v_mfma_f32_32x32x16_bf16 v[32:47], v[116:119], v[134:137], v[32:47]
	s_cbranch_scc1 .LBB0_1191
	v_add_u32_e32 v2, 0x4000003b, v1
	v_cmp_gt_u32_e32 vcc, 2.0, v2
	v_add_u32_e32 v2, 27, v1
	s_nop 0
	v_cndmask_b32_e32 v96, v179, v96, vcc
	v_cmp_lt_u32_e32 vcc, s96, v2
	v_add_u32_e32 v2, 58, v1
	s_nop 0
	v_cndmask_b32_e32 v80, v179, v80, vcc
	v_cmp_lt_u32_e32 vcc, s96, v2
	v_add_u32_e32 v2, 26, v1
	s_nop 0
	v_cndmask_b32_e32 v97, v179, v97, vcc
	v_cmp_lt_u32_e32 vcc, s96, v2
	v_add_u32_e32 v2, 57, v1
	s_nop 0
	v_cndmask_b32_e32 v81, v179, v81, vcc
	v_cmp_lt_u32_e32 vcc, s96, v2
	v_add_u32_e32 v2, 25, v1
	s_nop 0
	v_cndmask_b32_e32 v98, v179, v98, vcc
	v_cmp_lt_u32_e32 vcc, s96, v2
	v_add_u32_e32 v2, 56, v1
	s_nop 0
	v_cndmask_b32_e32 v82, v179, v82, vcc
	v_cmp_lt_u32_e32 vcc, s96, v2
	v_add_u32_e32 v2, 24, v1
	s_nop 0
	v_cndmask_b32_e32 v99, v179, v99, vcc
	v_cmp_lt_u32_e32 vcc, s96, v2
	v_add_u32_e32 v2, 51, v1
	s_nop 0
	v_cndmask_b32_e32 v83, v179, v83, vcc
	v_cmp_lt_u32_e32 vcc, s96, v2
	v_add_u32_e32 v2, 19, v1
	s_nop 0
	v_cndmask_b32_e32 v100, v179, v100, vcc
	v_cmp_lt_u32_e32 vcc, s96, v2
	v_add_u32_e32 v2, 50, v1
	s_nop 0
	v_cndmask_b32_e32 v84, v179, v84, vcc
	v_cmp_lt_u32_e32 vcc, s96, v2
	v_add_u32_e32 v2, 18, v1
	s_nop 0
	v_cndmask_b32_e32 v101, v179, v101, vcc
	v_cmp_lt_u32_e32 vcc, s96, v2
	v_add_u32_e32 v2, 49, v1
	s_nop 0
	v_cndmask_b32_e32 v85, v179, v85, vcc
	v_cmp_lt_u32_e32 vcc, s96, v2
	v_add_u32_e32 v2, 17, v1
	s_nop 0
	v_cndmask_b32_e32 v102, v179, v102, vcc
	v_cmp_lt_u32_e32 vcc, s96, v2
	v_add_u32_e32 v2, 48, v1
	s_nop 0
	v_cndmask_b32_e32 v86, v179, v86, vcc
	v_cmp_lt_u32_e32 vcc, s96, v2
	v_add_u32_e32 v2, 16, v1
	s_nop 0
	v_cndmask_b32_e32 v103, v179, v103, vcc
	v_cmp_lt_u32_e32 vcc, s96, v2
	v_add_u32_e32 v2, 43, v1
	s_nop 0
	v_cndmask_b32_e32 v87, v179, v87, vcc
	v_cmp_lt_u32_e32 vcc, s96, v2
	v_add_u32_e32 v2, 11, v1
	s_nop 0
	v_cndmask_b32_e32 v104, v179, v104, vcc
	v_cmp_lt_u32_e32 vcc, s96, v2
	v_add_u32_e32 v2, 42, v1
	s_nop 0
	v_cndmask_b32_e32 v88, v179, v88, vcc
	v_cmp_lt_u32_e32 vcc, s96, v2
	v_add_u32_e32 v2, 10, v1
	s_nop 0
	v_cndmask_b32_e32 v105, v179, v105, vcc
	v_cmp_lt_u32_e32 vcc, s96, v2
	v_add_u32_e32 v2, 41, v1
	s_nop 0
	v_cndmask_b32_e32 v89, v179, v89, vcc
	v_cmp_lt_u32_e32 vcc, s96, v2
	v_add_u32_e32 v2, 9, v1
	s_nop 0
	v_cndmask_b32_e32 v106, v179, v106, vcc
	v_cmp_lt_u32_e32 vcc, s96, v2
	v_add_u32_e32 v2, 40, v1
	s_nop 0
	v_cndmask_b32_e32 v90, v179, v90, vcc
	v_cmp_lt_u32_e32 vcc, s96, v2
	v_add_u32_e32 v2, 8, v1
	s_nop 0
	v_cndmask_b32_e32 v107, v179, v107, vcc
	v_cmp_lt_u32_e32 vcc, s96, v2
	v_add_u32_e32 v2, 35, v1
	s_nop 0
	v_cndmask_b32_e32 v91, v179, v91, vcc
	v_cmp_lt_u32_e32 vcc, s96, v2
	v_add_u32_e32 v2, 3, v1
	s_nop 0
	v_cndmask_b32_e32 v108, v179, v108, vcc
	v_cmp_lt_u32_e32 vcc, s96, v2
	v_add_u32_e32 v2, 34, v1
	s_nop 0
	v_cndmask_b32_e32 v92, v179, v92, vcc
	v_cmp_lt_u32_e32 vcc, s96, v2
	v_add_u32_e32 v2, 2, v1
	s_nop 0
	v_cndmask_b32_e32 v109, v179, v109, vcc
	v_cmp_lt_u32_e32 vcc, s96, v2
	v_add_u32_e32 v2, 33, v1
	s_nop 0
	v_cndmask_b32_e32 v93, v179, v93, vcc
	v_cmp_lt_u32_e32 vcc, s96, v2
	v_add_u32_e32 v2, 1, v1
	s_nop 0
	v_cndmask_b32_e32 v110, v179, v110, vcc
	v_cmp_lt_u32_e32 vcc, s96, v2
	v_add_u32_e32 v2, 32, v1
	s_nop 0
	v_cndmask_b32_e32 v94, v179, v94, vcc
	v_cmp_lt_u32_e32 vcc, s96, v2
	s_nop 1
	v_cndmask_b32_e32 v111, v179, v111, vcc
	v_cmp_lt_u32_e32 vcc, s96, v1
	s_nop 1
	v_cndmask_b32_e32 v95, v179, v95, vcc

.LBB0_1200:
	v_cndmask_b32_e64 v2, v2, v201, s[8:9]
	v_mul_f32_e32 v5, 0xbe0293ee, v2
	v_fmamk_f32 v7, v96, 0x3e0293ee, v5
	v_fmamk_f32 v8, v97, 0x3e0293ee, v5
	v_fmamk_f32 v9, v98, 0x3e0293ee, v5
	v_fmamk_f32 v10, v99, 0x3e0293ee, v5
	v_fmamk_f32 v11, v100, 0x3e0293ee, v5
	v_fmamk_f32 v12, v101, 0x3e0293ee, v5
	v_fmamk_f32 v13, v102, 0x3e0293ee, v5
	v_fmamk_f32 v14, v103, 0x3e0293ee, v5
	v_fmamk_f32 v15, v104, 0x3e0293ee, v5
	v_fmamk_f32 v96, v105, 0x3e0293ee, v5
	v_fmamk_f32 v97, v106, 0x3e0293ee, v5
	v_fmamk_f32 v98, v107, 0x3e0293ee, v5
	v_fmamk_f32 v99, v108, 0x3e0293ee, v5
	v_fmamk_f32 v100, v109, 0x3e0293ee, v5
	v_fmamk_f32 v101, v110, 0x3e0293ee, v5
	v_fmamk_f32 v102, v111, 0x3e0293ee, v5
	v_exp_f32_e32 v125, v7
	v_fmamk_f32 v7, v93, 0x3e0293ee, v5
	v_fmamk_f32 v112, v80, 0x3e0293ee, v5
	v_fmamk_f32 v113, v81, 0x3e0293ee, v5
	v_fmamk_f32 v114, v82, 0x3e0293ee, v5
	v_fmamk_f32 v115, v83, 0x3e0293ee, v5
	v_fmamk_f32 v116, v84, 0x3e0293ee, v5
	v_fmamk_f32 v117, v85, 0x3e0293ee, v5
	v_fmamk_f32 v118, v86, 0x3e0293ee, v5
	v_fmamk_f32 v119, v87, 0x3e0293ee, v5
	v_fmamk_f32 v120, v88, 0x3e0293ee, v5
	v_fmamk_f32 v121, v89, 0x3e0293ee, v5
	v_fmamk_f32 v122, v90, 0x3e0293ee, v5
	v_fmamk_f32 v123, v91, 0x3e0293ee, v5
	v_fmamk_f32 v124, v92, 0x3e0293ee, v5
	v_exp_f32_e32 v126, v8
	v_exp_f32_e32 v127, v9
	v_exp_f32_e32 v130, v10
	v_exp_f32_e32 v131, v11
	v_exp_f32_e32 v12, v12
	v_exp_f32_e32 v13, v13
	v_exp_f32_e32 v14, v14
	v_exp_f32_e32 v15, v15
	v_exp_f32_e32 v132, v96
	v_exp_f32_e32 v133, v97
	v_exp_f32_e32 v134, v98
	v_exp_f32_e32 v135, v99
	v_exp_f32_e32 v136, v100
	v_exp_f32_e32 v137, v101
	v_exp_f32_e32 v138, v102
	v_fmamk_f32 v139, v94, 0x3e0293ee, v5
	v_fmac_f32_e32 v5, 0x3e0293ee, v95
	s_ashr_i32 s1, s68, 8
	v_lshl_add_u32 v8, s1, 2, v128
	ds_read_b128 v[96:99], v8
	ds_read_b128 v[100:103], v8 offset:32
	ds_read_b128 v[80:83], v8 offset:128
	ds_read_b128 v[84:87], v8 offset:160
	ds_read_b128 v[104:107], v8 offset:64
	ds_read_b128 v[108:111], v8 offset:96
	ds_read_b128 v[88:91], v8 offset:192
	ds_read_b128 v[92:95], v8 offset:224
	s_add_i32 s1, s68, 0
	v_add3_u32 v140, s1, v197, v196
	v_add3_u32 v141, s1, v198, v196
	v_add3_u32 v142, s1, v199, v196
	v_add3_u32 v143, s1, v200, v196
	s_setprio 1
	ds_read_b128 v[8:11], v140 offset:49152
	ds_read_b128 v[220:223], v140 offset:57344
	ds_read_b128 v[224:227], v141 offset:49152
	ds_read_b128 v[228:231], v141 offset:57344
	ds_read_b128 v[232:235], v142 offset:49152
	s_waitcnt lgkmcnt(4)
	v_mfma_f32_32x32x16_bf16 v[96:111], v[8:11], v[172:175], v[96:111]
	ds_read_b128 v[8:11], v142 offset:57344
	s_waitcnt lgkmcnt(4)
	v_mfma_f32_32x32x16_bf16 v[80:95], v[220:223], v[172:175], v[80:95]
	ds_read_b128 v[220:223], v143 offset:49152
	s_waitcnt lgkmcnt(4)
	v_mfma_f32_32x32x16_bf16 v[96:111], v[224:227], v[168:171], v[96:111]
	ds_read_b128 v[224:227], v143 offset:57344
	s_waitcnt lgkmcnt(4)
	v_mfma_f32_32x32x16_bf16 v[80:95], v[228:231], v[168:171], v[80:95]
	ds_read_b128 v[228:231], v140 offset:49280
	s_waitcnt lgkmcnt(4)
	v_mfma_f32_32x32x16_bf16 v[96:111], v[232:235], v[164:167], v[96:111]
	ds_read_b128 v[232:235], v140 offset:57472
	s_waitcnt lgkmcnt(4)
	v_mfma_f32_32x32x16_bf16 v[80:95], v[8:11], v[164:167], v[80:95]
	ds_read_b128 v[8:11], v141 offset:49280
	s_waitcnt lgkmcnt(4)
	v_mfma_f32_32x32x16_bf16 v[96:111], v[220:223], v[160:163], v[96:111]
	ds_read_b128 v[220:223], v141 offset:57472
	s_waitcnt lgkmcnt(4)
	v_mfma_f32_32x32x16_bf16 v[80:95], v[224:227], v[160:163], v[80:95]
	ds_read_b128 v[224:227], v142 offset:49280
	s_waitcnt lgkmcnt(4)
	v_mfma_f32_32x32x16_bf16 v[96:111], v[228:231], v[156:159], v[96:111]
	ds_read_b128 v[228:231], v142 offset:57472
	s_waitcnt lgkmcnt(4)
	v_mfma_f32_32x32x16_bf16 v[80:95], v[232:235], v[156:159], v[80:95]
	ds_read_b128 v[232:235], v143 offset:49280
	s_waitcnt lgkmcnt(4)
	v_mfma_f32_32x32x16_bf16 v[96:111], v[8:11], v[152:155], v[96:111]
	ds_read_b128 v[8:11], v143 offset:57472
	s_waitcnt lgkmcnt(4)
	v_mfma_f32_32x32x16_bf16 v[80:95], v[220:223], v[152:155], v[80:95]
	s_waitcnt lgkmcnt(3)
	v_mfma_f32_32x32x16_bf16 v[96:111], v[224:227], v[148:151], v[96:111]
	s_waitcnt lgkmcnt(2)
	v_mfma_f32_32x32x16_bf16 v[80:95], v[228:231], v[148:151], v[80:95]
	s_waitcnt lgkmcnt(1)
	v_mfma_f32_32x32x16_bf16 v[96:111], v[232:235], v[144:147], v[96:111]
	s_waitcnt lgkmcnt(0)
	v_mfma_f32_32x32x16_bf16 v[80:95], v[8:11], v[144:147], v[80:95]
	s_setprio 0
	v_exp_f32_e32 v203, v7
	v_add_f32_e32 v7, 0, v125
	v_add_f32_e32 v7, v126, v7
	v_add_f32_e32 v7, v127, v7
	v_add_f32_e32 v7, v130, v7
	v_add_f32_e32 v7, v131, v7
	v_add_f32_e32 v7, v12, v7
	v_add_f32_e32 v7, v13, v7
	v_add_f32_e32 v7, v14, v7
	v_add_f32_e32 v7, v15, v7
	v_add_f32_e32 v7, v132, v7
	v_add_f32_e32 v7, v133, v7
	v_add_f32_e32 v7, v134, v7
	v_exp_f32_e32 v9, v112
	v_add_f32_e32 v7, v135, v7
	v_exp_f32_e32 v140, v113
	v_add_f32_e32 v7, v136, v7
	v_exp_f32_e32 v141, v114
	v_add_f32_e32 v7, v137, v7
	v_exp_f32_e32 v142, v115
	v_add_f32_e32 v7, v138, v7
	v_exp_f32_e32 v143, v116
	v_add_f32_e32 v7, v9, v7
	v_exp_f32_e32 v201, v117
	v_add_f32_e32 v7, v140, v7
	v_exp_f32_e32 v202, v118
	v_add_f32_e32 v7, v141, v7
	v_exp_f32_e32 v119, v119
	v_add_f32_e32 v7, v142, v7
	v_exp_f32_e32 v120, v120
	v_add_f32_e32 v7, v143, v7
	v_exp_f32_e32 v121, v121
	v_add_f32_e32 v7, v201, v7
	v_exp_f32_e32 v122, v122
	v_add_f32_e32 v7, v202, v7
	v_exp_f32_e32 v123, v123
	v_add_f32_e32 v7, v119, v7
	v_exp_f32_e32 v124, v124
	v_add_f32_e32 v7, v120, v7
	v_add_f32_e32 v7, v121, v7
	v_exp_f32_e32 v139, v139
	v_add_f32_e32 v7, v122, v7
	v_exp_f32_e32 v5, v5
	v_add_f32_e32 v7, v123, v7
	v_add_f32_e32 v7, v124, v7
	v_add_f32_e32 v7, v203, v7
	v_add_f32_e32 v7, v139, v7
	v_add_f32_e32 v7, v5, v7
	v_mov_b32_e32 v8, v7
	s_nop 1
	v_permlane32_swap_b32_e32 v7, v8
	v_cvt_pk_bf16_f32 v10, v125, v126
	v_cvt_pk_bf16_f32 v11, v127, v130
	v_cvt_pk_bf16_f32 v12, v131, v12
	v_cvt_pk_bf16_f32 v13, v13, v14
	v_cvt_pk_bf16_f32 v112, v15, v132
	v_cvt_pk_bf16_f32 v113, v133, v134
	v_cvt_pk_bf16_f32 v114, v135, v136
	v_cvt_pk_bf16_f32 v115, v137, v138
	v_cvt_pk_bf16_f32 v116, v9, v140
	v_cvt_pk_bf16_f32 v117, v141, v142
	v_cvt_pk_bf16_f32 v118, v143, v201
	v_cvt_pk_bf16_f32 v119, v202, v119
	v_cvt_pk_bf16_f32 v120, v120, v121
	v_cvt_pk_bf16_f32 v121, v122, v123
	v_cvt_pk_bf16_f32 v122, v124, v203
	v_cvt_pk_bf16_f32 v123, v139, v5
	s_nop 0
	v_permlane32_swap_b32_e32 v10, v12
	v_permlane32_swap_b32_e32 v11, v13
	v_permlane32_swap_b32_e32 v112, v114
	v_permlane32_swap_b32_e32 v113, v115
	v_permlane32_swap_b32_e32 v116, v118
	v_permlane32_swap_b32_e32 v117, v119
	v_permlane32_swap_b32_e32 v120, v122
	v_permlane32_swap_b32_e32 v121, v123
	v_add_u32_e32 v5, s66, v193
	ds_read_b64_tr_b16 v[124:125], v5 offset:0
	ds_read_b64_tr_b16 v[126:127], v5 offset:0x800
	ds_read_b64_tr_b16 v[130:131], v5 offset:0x1000
	ds_read_b64_tr_b16 v[132:133], v5 offset:0x1800
	ds_read_b64_tr_b16 v[134:135], v5 offset:0x2000
	ds_read_b64_tr_b16 v[136:137], v5 offset:0x2800
	ds_read_b64_tr_b16 v[138:139], v5 offset:0x3000
	ds_read_b64_tr_b16 v[140:141], v5 offset:0x3800
	s_waitcnt lgkmcnt(0)
	s_nop 0
	v_mfma_f32_32x32x16_bf16 v[16:31], v[10:13], v[124:127], v[16:31]
	ds_read_b64_tr_b16 v[124:125], v5 offset:0x200
	ds_read_b64_tr_b16 v[126:127], v5 offset:0xa00
	v_mfma_f32_32x32x16_bf16 v[16:31], v[112:115], v[130:133], v[16:31]
	ds_read_b64_tr_b16 v[130:131], v5 offset:0x1200
	ds_read_b64_tr_b16 v[132:133], v5 offset:0x1a00
	v_mfma_f32_32x32x16_bf16 v[16:31], v[116:119], v[134:137], v[16:31]
	ds_read_b64_tr_b16 v[134:135], v5 offset:0x2200
	ds_read_b64_tr_b16 v[136:137], v5 offset:0x2a00
	v_mfma_f32_32x32x16_bf16 v[16:31], v[120:123], v[138:141], v[16:31]
	ds_read_b64_tr_b16 v[138:139], v5 offset:0x3200
	ds_read_b64_tr_b16 v[140:141], v5 offset:0x3a00
	s_waitcnt lgkmcnt(0)
	v_mfma_f32_32x32x16_bf16 v[48:63], v[10:13], v[124:127], v[48:63]
	ds_read_b64_tr_b16 v[124:125], v5 offset:0x400
	ds_read_b64_tr_b16 v[126:127], v5 offset:0xc00
	v_mfma_f32_32x32x16_bf16 v[48:63], v[112:115], v[130:133], v[48:63]
	ds_read_b64_tr_b16 v[130:131], v5 offset:0x1400
	ds_read_b64_tr_b16 v[132:133], v5 offset:0x1c00
	v_mfma_f32_32x32x16_bf16 v[48:63], v[116:119], v[134:137], v[48:63]
	ds_read_b64_tr_b16 v[134:135], v5 offset:0x2400
	ds_read_b64_tr_b16 v[136:137], v5 offset:0x2c00
	v_mfma_f32_32x32x16_bf16 v[48:63], v[120:123], v[138:141], v[48:63]
	ds_read_b64_tr_b16 v[138:139], v5 offset:0x3400
	ds_read_b64_tr_b16 v[140:141], v5 offset:0x3c00
	s_waitcnt lgkmcnt(0)
	v_mfma_f32_32x32x16_bf16 v[64:79], v[10:13], v[124:127], v[64:79]
	ds_read_b64_tr_b16 v[124:125], v5 offset:0x600
	ds_read_b64_tr_b16 v[126:127], v5 offset:0xe00
	v_mfma_f32_32x32x16_bf16 v[64:79], v[112:115], v[130:133], v[64:79]
	ds_read_b64_tr_b16 v[130:131], v5 offset:0x1600
	ds_read_b64_tr_b16 v[132:133], v5 offset:0x1e00
	v_mfma_f32_32x32x16_bf16 v[64:79], v[116:119], v[134:137], v[64:79]
	ds_read_b64_tr_b16 v[134:135], v5 offset:0x2600
	ds_read_b64_tr_b16 v[136:137], v5 offset:0x2e00
	v_mfma_f32_32x32x16_bf16 v[64:79], v[120:123], v[138:141], v[64:79]
	ds_read_b64_tr_b16 v[138:139], v5 offset:0x3600
	ds_read_b64_tr_b16 v[140:141], v5 offset:0x3e00
	s_waitcnt lgkmcnt(0)
	v_mfma_f32_32x32x16_bf16 v[32:47], v[10:13], v[124:127], v[32:47]
	s_cmp_le_i32 s70, s69
	v_mfma_f32_32x32x16_bf16 v[32:47], v[112:115], v[130:133], v[32:47]
	v_mfma_f32_32x32x16_bf16 v[32:47], v[116:119], v[134:137], v[32:47]
	v_mfma_f32_32x32x16_bf16 v[32:47], v[120:123], v[138:141], v[32:47]
	s_cbranch_scc1 .LBB0_1202
	v_add_u32_e32 v5, 0x4000007b, v1
	v_cmp_gt_u32_e32 vcc, 2.0, v5
	v_add_u32_e32 v5, 0x5b, v1
	s_nop 0
	v_cndmask_b32_e32 v96, v179, v96, vcc
	v_cmp_lt_u32_e32 vcc, s96, v5
	v_add_u32_e32 v5, 0x7a, v1
	s_nop 0
	v_cndmask_b32_e32 v80, v179, v80, vcc
	v_cmp_lt_u32_e32 vcc, s96, v5
	v_add_u32_e32 v5, 0x5a, v1
	s_nop 0
	v_cndmask_b32_e32 v97, v179, v97, vcc
	v_cmp_lt_u32_e32 vcc, s96, v5
	v_add_u32_e32 v5, 0x79, v1
	s_nop 0
	v_cndmask_b32_e32 v81, v179, v81, vcc
	v_cmp_lt_u32_e32 vcc, s96, v5
	v_add_u32_e32 v5, 0x59, v1
	s_nop 0
	v_cndmask_b32_e32 v98, v179, v98, vcc
	v_cmp_lt_u32_e32 vcc, s96, v5
	v_add_u32_e32 v5, 0x78, v1
	s_nop 0
	v_cndmask_b32_e32 v82, v179, v82, vcc
	v_cmp_lt_u32_e32 vcc, s96, v5
	v_add_u32_e32 v5, 0x58, v1
	s_nop 0
	v_cndmask_b32_e32 v99, v179, v99, vcc
	v_cmp_lt_u32_e32 vcc, s96, v5
	v_add_u32_e32 v5, 0x73, v1
	s_nop 0
	v_cndmask_b32_e32 v83, v179, v83, vcc
	v_cmp_lt_u32_e32 vcc, s96, v5
	v_add_u32_e32 v5, 0x53, v1
	s_nop 0
	v_cndmask_b32_e32 v100, v179, v100, vcc
	v_cmp_lt_u32_e32 vcc, s96, v5
	v_add_u32_e32 v5, 0x72, v1
	s_nop 0
	v_cndmask_b32_e32 v84, v179, v84, vcc
	v_cmp_lt_u32_e32 vcc, s96, v5
	v_add_u32_e32 v5, 0x52, v1
	s_nop 0
	v_cndmask_b32_e32 v101, v179, v101, vcc
	v_cmp_lt_u32_e32 vcc, s96, v5
	v_add_u32_e32 v5, 0x71, v1
	s_nop 0
	v_cndmask_b32_e32 v85, v179, v85, vcc
	v_cmp_lt_u32_e32 vcc, s96, v5
	v_add_u32_e32 v5, 0x51, v1
	s_nop 0
	v_cndmask_b32_e32 v102, v179, v102, vcc
	v_cmp_lt_u32_e32 vcc, s96, v5
	v_add_u32_e32 v5, 0x70, v1
	s_nop 0
	v_cndmask_b32_e32 v86, v179, v86, vcc
	v_cmp_lt_u32_e32 vcc, s96, v5
	v_add_u32_e32 v5, 0x50, v1
	s_nop 0
	v_cndmask_b32_e32 v103, v179, v103, vcc
	v_cmp_lt_u32_e32 vcc, s96, v5
	v_add_u32_e32 v5, 0x6b, v1
	s_nop 0
	v_cndmask_b32_e32 v87, v179, v87, vcc
	v_cmp_lt_u32_e32 vcc, s96, v5
	v_add_u32_e32 v5, 0x4b, v1
	s_nop 0
	v_cndmask_b32_e32 v104, v179, v104, vcc
	v_cmp_lt_u32_e32 vcc, s96, v5
	v_add_u32_e32 v5, 0x6a, v1
	s_nop 0
	v_cndmask_b32_e32 v88, v179, v88, vcc
	v_cmp_lt_u32_e32 vcc, s96, v5
	v_add_u32_e32 v5, 0x4a, v1
	s_nop 0
	v_cndmask_b32_e32 v105, v179, v105, vcc
	v_cmp_lt_u32_e32 vcc, s96, v5
	v_add_u32_e32 v5, 0x69, v1
	s_nop 0
	v_cndmask_b32_e32 v89, v179, v89, vcc
	v_cmp_lt_u32_e32 vcc, s96, v5
	v_add_u32_e32 v5, 0x49, v1
	s_nop 0
	v_cndmask_b32_e32 v106, v179, v106, vcc
	v_cmp_lt_u32_e32 vcc, s96, v5
	v_add_u32_e32 v5, 0x68, v1
	s_nop 0
	v_cndmask_b32_e32 v90, v179, v90, vcc
	v_cmp_lt_u32_e32 vcc, s96, v5
	v_add_u32_e32 v5, 0x48, v1
	s_nop 0
	v_cndmask_b32_e32 v107, v179, v107, vcc
	v_cmp_lt_u32_e32 vcc, s96, v5
	v_add_u32_e32 v5, 0x63, v1
	s_nop 0
	v_cndmask_b32_e32 v91, v179, v91, vcc
	v_cmp_lt_u32_e32 vcc, s96, v5
	v_add_u32_e32 v5, 0x43, v1
	s_nop 0
	v_cndmask_b32_e32 v108, v179, v108, vcc
	v_cmp_lt_u32_e32 vcc, s96, v5
	v_add_u32_e32 v5, 0x62, v1
	s_nop 0
	v_cndmask_b32_e32 v92, v179, v92, vcc
	v_cmp_lt_u32_e32 vcc, s96, v5
	v_add_u32_e32 v5, 0x42, v1
	s_nop 0
	v_cndmask_b32_e32 v109, v179, v109, vcc
	v_cmp_lt_u32_e32 vcc, s96, v5
	v_add_u32_e32 v5, 0x61, v1
	s_nop 0
	v_cndmask_b32_e32 v93, v179, v93, vcc
	v_cmp_lt_u32_e32 vcc, s96, v5
	v_add_u32_e32 v5, 0x41, v1
	s_nop 0
	v_cndmask_b32_e32 v110, v179, v110, vcc
	v_cmp_lt_u32_e32 vcc, s96, v5
	v_add_u32_e32 v5, 0x60, v1
	s_nop 0
	v_cndmask_b32_e32 v94, v179, v94, vcc
	v_cmp_lt_u32_e32 vcc, s96, v5
	v_add_u32_e32 v5, 64, v1
	s_nop 0
	v_cndmask_b32_e32 v111, v179, v111, vcc
	v_cmp_lt_u32_e32 vcc, s96, v5
	s_nop 1
	v_cndmask_b32_e32 v95, v179, v95, vcc
